# S1 phase: the 48 GEMM workgroups hand 2 of their 4 conv tiles to workgroups 128..223
# baseline (speedup 1.0000x reference)
.LBB7_803:
	s_or_b64 exec, exec, s[6:7]
	v_readlane_b32 s4, v252, 7
	v_readlane_b32 s5, v252, 8
	s_andn2_b64 vcc, exec, s[4:5]
	s_cbranch_vccnz .LBB7_813
	s_load_dwordx8 s[12:19], s[42:43], 0xa0
	v_readlane_b32 s4, v250, 10
	v_readlane_b32 s5, v250, 11
	s_lshl_b64 s[4:5], s[4:5], 2
	v_readlane_b32 s3, v250, 27
	s_waitcnt lgkmcnt(0)
	s_add_u32 s6, s18, s4
	s_addc_u32 s7, s19, s5
	s_add_u32 s8, s16, s4
	s_addc_u32 s9, s17, s5
	s_add_u32 s12, s12, s3
	s_movk_i32 s3, 0xba0
	s_addc_u32 s13, s13, 0
	v_cmp_gt_i32_e32 vcc, s3, v150
	s_movk_i32 s3, 0x180
	s_add_u32 s4, s14, s4
	v_cmp_gt_i32_e64 s[40:41], s3, v150
	v_ashrrev_i32_e32 v151, 31, v150
	v_lshlrev_b32_e32 v0, 2, v150
	v_readlane_b32 s3, v253, 39
	s_addc_u32 s5, s15, s5
	v_lshlrev_b64 v[2:3], 2, v[150:151]
	v_add_u32_e32 v108, 0, v0
	v_add_u32_e32 v109, s3, v0
	v_mov_b32_e32 v0, s3
	v_lshl_add_u64 v[10:11], s[4:5], 0, v[2:3]
	v_mad_u64_u32 v[12:13], s[4:5], v204, 24, v[0:1]
	v_lshl_add_u64 v[14:15], s[12:13], 0, v[2:3]
	s_mov_b64 s[4:5], 0x1200
	v_lshl_add_u64 v[16:17], v[14:15], 0, s[4:5]
	s_mov_b64 s[4:5], 0x1800
	v_lshl_add_u64 v[18:19], v[14:15], 0, s[4:5]
	s_mov_b64 s[4:5], 0x1e00
	v_lshl_add_u64 v[20:21], v[14:15], 0, s[4:5]
	s_mov_b64 s[4:5], 0x2400
	v_lshl_add_u64 v[22:23], v[14:15], 0, s[4:5]
	s_mov_b64 s[4:5], 0x2a00
	v_lshl_add_u64 v[24:25], v[14:15], 0, s[4:5]
	s_mov_b64 s[4:5], 0x3000
	v_lshl_add_u64 v[26:27], v[14:15], 0, s[4:5]
	s_mov_b64 s[4:5], 0x3600
	v_and_b32_e32 v0, 64, v163
	v_lshl_add_u64 v[28:29], v[14:15], 0, s[4:5]
	s_mov_b64 s[4:5], 0x3c00
	v_add_u32_e32 v0, 64, v0
	v_xor_b32_e32 v4, 1, v163
	v_lshl_add_u64 v[30:31], v[14:15], 0, s[4:5]
	s_mov_b64 s[4:5], 0x4200
	v_cmp_lt_i32_e64 s[42:43], v4, v0
	v_lshl_add_u64 v[32:33], v[14:15], 0, s[4:5]
	s_mov_b64 s[4:5], 0x4800
	v_cndmask_b32_e64 v4, v163, v4, s[42:43]
	v_lshl_add_u64 v[34:35], v[14:15], 0, s[4:5]
	s_mov_b64 s[4:5], 0x4e00
	v_lshlrev_b32_e32 v13, 2, v4
	v_xor_b32_e32 v4, 2, v163
	v_lshl_add_u64 v[36:37], v[14:15], 0, s[4:5]
	s_mov_b64 s[4:5], 0x5400
	v_cmp_lt_i32_e64 s[42:43], v4, v0
	v_lshl_add_u64 v[38:39], v[14:15], 0, s[4:5]
	s_mov_b64 s[4:5], 0x5a00
	v_cndmask_b32_e64 v4, v163, v4, s[42:43]
	v_lshl_add_u64 v[40:41], v[14:15], 0, s[4:5]
	s_mov_b64 s[4:5], 0x6000
	v_lshlrev_b32_e32 v110, 2, v4
	v_xor_b32_e32 v4, 4, v163
	v_lshl_add_u64 v[42:43], v[14:15], 0, s[4:5]
	s_mov_b64 s[4:5], 0x6600
	v_cmp_lt_i32_e64 s[42:43], v4, v0
	v_lshl_add_u64 v[44:45], v[14:15], 0, s[4:5]
	s_mov_b64 s[4:5], 0x6c00
	v_cndmask_b32_e64 v4, v163, v4, s[42:43]
	v_lshl_add_u64 v[46:47], v[14:15], 0, s[4:5]
	s_mov_b64 s[4:5], 0x7200
	v_lshlrev_b32_e32 v111, 2, v4
	v_xor_b32_e32 v4, 8, v163
	v_lshl_add_u64 v[48:49], v[14:15], 0, s[4:5]
	s_mov_b64 s[4:5], 0x7800
	v_cmp_lt_i32_e64 s[42:43], v4, v0
	v_lshl_add_u64 v[50:51], v[14:15], 0, s[4:5]
	s_mov_b64 s[4:5], 0x7e00
	v_cndmask_b32_e64 v4, v163, v4, s[42:43]
	v_lshl_add_u64 v[52:53], v[14:15], 0, s[4:5]
	s_mov_b64 s[4:5], 0x8400
	v_lshlrev_b32_e32 v112, 2, v4
	v_xor_b32_e32 v4, 16, v163
	v_lshl_add_u64 v[54:55], v[14:15], 0, s[4:5]
	s_mov_b64 s[4:5], 0x8a00
	v_cmp_lt_i32_e64 s[42:43], v4, v0
	v_lshl_add_u64 v[56:57], v[14:15], 0, s[4:5]
	s_mov_b64 s[4:5], 0x9000
	v_cndmask_b32_e64 v4, v163, v4, s[42:43]
	v_lshl_add_u64 v[58:59], v[14:15], 0, s[4:5]
	s_mov_b64 s[4:5], 0x9600
	v_lshlrev_b32_e32 v113, 2, v4
	v_xor_b32_e32 v4, 32, v163
	v_lshl_add_u64 v[60:61], v[14:15], 0, s[4:5]
	s_mov_b64 s[4:5], 0x9c00
	v_cmp_lt_i32_e64 s[42:43], v4, v0
	v_lshl_add_u64 v[62:63], v[14:15], 0, s[4:5]
	s_mov_b64 s[4:5], 0xa200
	v_cndmask_b32_e64 v0, v163, v4, s[42:43]
	v_mul_lo_u32 v4, v204, 6
	v_lshl_add_u64 v[64:65], v[14:15], 0, s[4:5]
	s_mov_b64 s[4:5], 0xa800
	v_ashrrev_i32_e32 v5, 31, v4
	v_lshl_add_u64 v[66:67], v[14:15], 0, s[4:5]
	s_mov_b64 s[4:5], 0xae00
	v_lshl_add_u64 v[68:69], v[14:15], 0, s[4:5]
	s_mov_b64 s[4:5], 0xb400
	v_lshlrev_b64 v[2:3], 2, v[4:5]
	v_lshlrev_b32_e32 v114, 2, v0
	v_lshl_add_u64 v[70:71], v[14:15], 0, s[4:5]
	v_add_u32_e32 v115, 0x10200, v108
	v_add_u32_e32 v116, 0x10800, v108
	v_add_u32_e32 v117, 0x10e00, v108
	v_add_u32_e32 v118, 0x11400, v108
	v_add_u32_e32 v119, 0x11a00, v108
	v_add_u32_e32 v120, 0x12000, v108
	v_add_u32_e32 v121, 0x12600, v108
	v_add_u32_e32 v122, 0x12c00, v108
	v_add_u32_e32 v123, 0x13200, v108
	v_add_u32_e32 v124, 0x13800, v108
	v_add_u32_e32 v125, 0x13e00, v108
	v_add_u32_e32 v126, 0x14400, v108
	v_add_u32_e32 v127, 0x14a00, v108
	v_add_u32_e32 v128, 0x15000, v108
	v_add_u32_e32 v129, 0x15600, v108
	v_add_u32_e32 v130, 0x15c00, v108
	v_add_u32_e32 v131, 0x16200, v108
	v_add_u32_e32 v132, 0x16800, v108
	v_add_u32_e32 v133, 0x16e00, v108
	v_lshl_add_u64 v[72:73], s[8:9], 0, v[2:3]
	v_lshl_add_u64 v[74:75], s[6:7], 0, v[2:3]
	v_lshl_add_u64 v[76:77], v[4:5], 1, s[0:1]
	s_and_saveexec_b64 s[4:5], s[40:41]
	global_load_dword v247, v[10:11], off
	global_load_dword v216, v[14:15], off
	global_load_dword v217, v[14:15], off offset:1536
	global_load_dword v218, v[14:15], off offset:3072
	global_load_dword v219, v[16:17], off
	global_load_dword v220, v[18:19], off
	global_load_dword v221, v[20:21], off
	global_load_dword v222, v[22:23], off
	global_load_dword v223, v[24:25], off
	global_load_dword v224, v[26:27], off
	global_load_dword v225, v[28:29], off
	global_load_dword v226, v[30:31], off
	global_load_dword v227, v[32:33], off
	global_load_dword v228, v[34:35], off
	global_load_dword v229, v[36:37], off
	global_load_dword v230, v[38:39], off
	global_load_dword v231, v[40:41], off
	global_load_dword v232, v[42:43], off
	global_load_dword v233, v[44:45], off
	global_load_dword v234, v[46:47], off
	global_load_dword v235, v[48:49], off
	global_load_dword v236, v[50:51], off
	global_load_dword v237, v[52:53], off
	global_load_dword v238, v[54:55], off
	global_load_dword v239, v[56:57], off
	global_load_dword v240, v[58:59], off
	global_load_dword v241, v[60:61], off
	global_load_dword v242, v[62:63], off
	global_load_dword v243, v[64:65], off
	global_load_dword v244, v[66:67], off
	global_load_dword v245, v[68:69], off
	global_load_dword v246, v[70:71], off
	s_or_b64 exec, exec, s[4:5]
	s_waitcnt vmcnt(0)
	global_load_dwordx4 v[14:17], v[72:73], off
	global_load_dwordx2 v[18:19], v[72:73], off offset:16
	global_load_dwordx4 v[20:23], v[74:75], off
	global_load_dwordx2 v[10:11], v[74:75], off offset:16
	s_waitcnt vmcnt(0)
	s_mov_b32 s12, s2
	s_movk_i32 s100, 0x400
	s_movk_i32 s101, 0x4000
	s_cmpk_eq_u32 s60, 0x100
	s_cbranch_scc0 .Lct_plain
	s_cmp_lt_u32 s2, 48
	s_cselect_b32 s100, 0x200, s100
	s_sub_u32 s15, s2, 0x80
	s_cmp_lt_u32 s15, 96
	s_cbranch_scc0 .Lct_plain
	s_add_u32 s101, s15, 0x200
	s_cmp_lt_u32 s15, 48
	s_cbranch_scc1 .Lct_plain
	s_add_u32 s101, s15, 0x2d0
.Lct_plain:
	s_movk_i32 s14, 0x1a0
	v_cmp_gt_i32_e64 s[6:7], s14, v150
	s_lshl_b32 s15, s12, 5
	s_and_b32 s3, s15, 0x7e0
	s_sub_i32 s3, 29, s3
	s_sub_i32 s4, s15, 30
	s_mov_b32 s5, 0x2aaaaaab
	s_movk_i32 s14, 0xfe80
	v_mov_b32_e32 v79, v150
	v_mul_hi_i32 v80, v79, s5
	v_lshrrev_b32_e32 v81, 31, v80
	v_ashrrev_i32_e32 v80, 3, v80
	v_add_u32_e32 v80, v80, v81
	v_cmp_lt_i32_e64 s[42:43], s3, v80
	s_nop 1
	s_and_saveexec_b64 s[8:9], s[42:43]
	v_add_u32_e32 v82, s4, v80
	v_ashrrev_i32_e32 v83, 31, v82
	v_lshlrev_b64 v[82:83], 11, v[82:83]
	v_lshl_add_u64 v[82:83], s[44:45], 0, v[82:83]
	v_lshlrev_b32_e32 v84, 3, v79
	v_mad_i32_i24 v84, v80, s14, v84
	v_mov_b32_e32 v85, 0
	v_lshl_add_u64 v[82:83], v[84:85], 1, v[82:83]
	global_load_dwordx4 v[24:27], v[82:83], off offset:512
	global_load_dwordx4 v[28:31], v[82:83], off offset:1280
	s_or_b64 exec, exec, s[8:9]
	v_add_u32_e32 v79, 512, v150
	v_mul_hi_i32 v80, v79, s5
	v_lshrrev_b32_e32 v81, 31, v80
	v_ashrrev_i32_e32 v80, 3, v80
	v_add_u32_e32 v80, v80, v81
	v_cmp_lt_i32_e64 s[42:43], s3, v80
	s_nop 1
	s_and_saveexec_b64 s[8:9], s[42:43]
	v_add_u32_e32 v82, s4, v80
	v_ashrrev_i32_e32 v83, 31, v82
	v_lshlrev_b64 v[82:83], 11, v[82:83]
	v_lshl_add_u64 v[82:83], s[44:45], 0, v[82:83]
	v_lshlrev_b32_e32 v84, 3, v79
	v_mad_i32_i24 v84, v80, s14, v84
	v_mov_b32_e32 v85, 0
	v_lshl_add_u64 v[82:83], v[84:85], 1, v[82:83]
	global_load_dwordx4 v[32:35], v[82:83], off offset:512
	global_load_dwordx4 v[36:39], v[82:83], off offset:1280
	s_or_b64 exec, exec, s[8:9]
	v_add_u32_e32 v79, 1024, v150
	v_mul_hi_i32 v80, v79, s5
	v_lshrrev_b32_e32 v81, 31, v80
	v_ashrrev_i32_e32 v80, 3, v80
	v_add_u32_e32 v80, v80, v81
	v_cmp_lt_i32_e64 s[42:43], s3, v80
	s_nop 1
	s_and_saveexec_b64 s[8:9], s[42:43]
	v_add_u32_e32 v82, s4, v80
	v_ashrrev_i32_e32 v83, 31, v82
	v_lshlrev_b64 v[82:83], 11, v[82:83]
	v_lshl_add_u64 v[82:83], s[44:45], 0, v[82:83]
	v_lshlrev_b32_e32 v84, 3, v79
	v_mad_i32_i24 v84, v80, s14, v84
	v_mov_b32_e32 v85, 0
	v_lshl_add_u64 v[82:83], v[84:85], 1, v[82:83]
	global_load_dwordx4 v[40:43], v[82:83], off offset:512
	global_load_dwordx4 v[44:47], v[82:83], off offset:1280
	s_or_b64 exec, exec, s[8:9]
	v_add_u32_e32 v79, 1536, v150
	v_mul_hi_i32 v80, v79, s5
	v_lshrrev_b32_e32 v81, 31, v80
	v_ashrrev_i32_e32 v80, 3, v80
	v_add_u32_e32 v80, v80, v81
	v_cmp_lt_i32_e64 s[42:43], s3, v80
	s_nop 1
	s_and_saveexec_b64 s[8:9], s[42:43]
	v_add_u32_e32 v82, s4, v80
	v_ashrrev_i32_e32 v83, 31, v82
	v_lshlrev_b64 v[82:83], 11, v[82:83]
	v_lshl_add_u64 v[82:83], s[44:45], 0, v[82:83]
	v_lshlrev_b32_e32 v84, 3, v79
	v_mad_i32_i24 v84, v80, s14, v84
	v_mov_b32_e32 v85, 0
	v_lshl_add_u64 v[82:83], v[84:85], 1, v[82:83]
	global_load_dwordx4 v[48:51], v[82:83], off offset:512
	global_load_dwordx4 v[52:55], v[82:83], off offset:1280
	s_or_b64 exec, exec, s[8:9]
	v_add_u32_e32 v79, 2048, v150
	v_mul_hi_i32 v80, v79, s5
	v_lshrrev_b32_e32 v81, 31, v80
	v_ashrrev_i32_e32 v80, 3, v80
	v_add_u32_e32 v80, v80, v81
	v_cmp_lt_i32_e64 s[42:43], s3, v80
	s_nop 1
	s_and_saveexec_b64 s[8:9], s[42:43]
	v_add_u32_e32 v82, s4, v80
	v_ashrrev_i32_e32 v83, 31, v82
	v_lshlrev_b64 v[82:83], 11, v[82:83]
	v_lshl_add_u64 v[82:83], s[44:45], 0, v[82:83]
	v_lshlrev_b32_e32 v84, 3, v79
	v_mad_i32_i24 v84, v80, s14, v84
	v_mov_b32_e32 v85, 0
	v_lshl_add_u64 v[82:83], v[84:85], 1, v[82:83]
	global_load_dwordx4 v[56:59], v[82:83], off offset:512
	global_load_dwordx4 v[60:63], v[82:83], off offset:1280
	s_or_b64 exec, exec, s[8:9]
	v_add_u32_e32 v79, 2560, v150
	v_mul_hi_i32 v80, v79, s5
	v_lshrrev_b32_e32 v81, 31, v80
	v_ashrrev_i32_e32 v80, 3, v80
	v_add_u32_e32 v80, v80, v81
	v_cmp_lt_i32_e64 s[42:43], s3, v80
	s_nop 1
	s_and_b64 s[42:43], s[42:43], s[6:7]
	s_and_saveexec_b64 s[8:9], s[42:43]
	v_add_u32_e32 v82, s4, v80
	v_ashrrev_i32_e32 v83, 31, v82
	v_lshlrev_b64 v[82:83], 11, v[82:83]
	v_lshl_add_u64 v[82:83], s[44:45], 0, v[82:83]
	v_lshlrev_b32_e32 v84, 3, v79
	v_mad_i32_i24 v84, v80, s14, v84
	v_mov_b32_e32 v85, 0
	v_lshl_add_u64 v[82:83], v[84:85], 1, v[82:83]
	global_load_dwordx4 v[64:67], v[82:83], off offset:512
	global_load_dwordx4 v[68:71], v[82:83], off offset:1280
	s_or_b64 exec, exec, s[8:9]
	s_branch .LBB7_806
.LBB7_805:
	s_or_b64 exec, exec, s[0:1]
	v_add_u32_e32 v0, s31, v12
	s_waitcnt lgkmcnt(0)
	s_barrier
	ds_read2_b64 v[2:5], v0 offset1:1
	s_add_i32 s0, s13, s86
	s_ashr_i32 s1, s0, 31
	s_lshl_b64 s[0:1], s[0:1], 11
	s_add_i32 s12, s12, s60
	s_cmp_lt_i32 s12, s100
	s_cbranch_scc1 .Lct_ok
	s_mov_b32 s12, s101
	s_movk_i32 s101, 0x4000
	s_mov_b32 s100, 0
.Lct_ok:
	s_waitcnt lgkmcnt(0)
	v_add_f32_e32 v6, 0, v2
	v_add_f32_e32 v8, v6, v3
	ds_read_b64 v[6:7], v0 offset:16
	v_add_f32_e32 v0, v8, v4
	v_add_f32_e32 v0, v0, v5
	s_waitcnt lgkmcnt(0)
	v_add_f32_e32 v0, v0, v6
	v_add_f32_e32 v0, v0, v7
	s_nop 0
	s_waitcnt lgkmcnt(0)
	s_nop 1
	v_add_f32_dpp v0, v0, v0 quad_perm:[1,0,3,2] row_mask:0xf bank_mask:0xf
	s_nop 0
	s_waitcnt lgkmcnt(0)
	s_nop 1
	v_add_f32_dpp v0, v0, v0 quad_perm:[2,3,0,1] row_mask:0xf bank_mask:0xf
	s_nop 0
	s_waitcnt lgkmcnt(0)
	s_nop 1
	v_add_f32_dpp v0, v0, v0 row_half_mirror row_mask:0xf bank_mask:0xf
	s_nop 0
	s_waitcnt lgkmcnt(0)
	s_nop 1
	v_add_f32_dpp v0, v0, v0 row_mirror row_mask:0xf bank_mask:0xf
	v_mov_b32_e32 v8, v0
	s_nop 1
	v_permlane16_swap_b32_e32 v0, v8
	s_waitcnt lgkmcnt(0)
	v_add_f32_e32 v0, v0, v8
	v_mov_b32_e32 v8, v0
	s_nop 1
	v_permlane32_swap_b32_e32 v0, v8
	s_waitcnt lgkmcnt(0)
	v_add_f32_e32 v8, v0, v8
	v_mul_f32_e32 v0, 0x3b2aaaab, v8
	v_fmac_f32_e32 v3, 0xbb2aaaab, v8
	v_fmamk_f32 v2, v8, 0xbb2aaaab, v2
	v_mul_f32_e32 v78, v3, v3
	v_pk_add_f32 v[8:9], v[4:5], v[0:1] op_sel_hi:[1,0] neg_lo:[0,1] neg_hi:[0,1]
	v_fmac_f32_e32 v78, v2, v2
	v_pk_mul_f32 v[4:5], v[8:9], v[8:9]
	v_pk_add_f32 v[82:83], v[6:7], v[0:1] op_sel_hi:[1,0] neg_lo:[0,1] neg_hi:[0,1]
	v_add_f32_e32 v4, v4, v78
	v_add_f32_e32 v78, v5, v4
	v_pk_mul_f32 v[4:5], v[82:83], v[82:83]
	s_nop 0
	v_add_f32_e32 v0, v4, v78
	v_add_f32_e32 v0, v5, v0
	s_nop 0
	s_waitcnt lgkmcnt(0)
	s_nop 1
	v_add_f32_dpp v0, v0, v0 quad_perm:[1,0,3,2] row_mask:0xf bank_mask:0xf
	s_nop 0
	s_waitcnt lgkmcnt(0)
	s_nop 1
	v_add_f32_dpp v0, v0, v0 quad_perm:[2,3,0,1] row_mask:0xf bank_mask:0xf
	s_nop 0
	s_waitcnt lgkmcnt(0)
	s_nop 1
	v_add_f32_dpp v0, v0, v0 row_half_mirror row_mask:0xf bank_mask:0xf
	s_nop 0
	s_waitcnt lgkmcnt(0)
	s_nop 1
	v_add_f32_dpp v0, v0, v0 row_mirror row_mask:0xf bank_mask:0xf
	v_mov_b32_e32 v4, v0
	s_nop 1
	v_permlane16_swap_b32_e32 v0, v4
	s_waitcnt lgkmcnt(0)
	v_add_f32_e32 v0, v0, v4
	v_mov_b32_e32 v4, v0
	s_nop 1
	v_permlane32_swap_b32_e32 v0, v4
	s_waitcnt lgkmcnt(0)
	v_add_f32_e32 v0, v0, v4
	v_fmamk_f32 v0, v0, 0x3b2aaaab, v162
	v_cmp_gt_f32_e64 s[42:43], s11, v0
	v_mul_f32_e32 v4, 0x4b800000, v0
	s_nop 0
	v_cndmask_b32_e64 v0, v0, v4, s[42:43]
	v_rsq_f32_e32 v0, v0
	s_nop 0
	v_mul_f32_e32 v4, 0x45800000, v0
	v_cndmask_b32_e64 v0, v0, v4, s[42:43]
	v_mul_f32_e32 v2, v2, v0
	v_fma_f32 v2, v14, v2, v20
	v_mul_f32_e32 v4, 0xbfb8aa3b, v2
	v_exp_f32_e32 v4, v4
	s_nop 0
	v_add_f32_e32 v4, 1.0, v4
	v_rcp_f32_e32 v4, v4
	s_nop 0
	v_mul_f32_e32 v4, v2, v4
	v_mul_f32_e32 v2, v3, v0
	v_fma_f32 v2, v15, v2, v21
	v_mul_f32_e32 v3, 0xbfb8aa3b, v2
	v_exp_f32_e32 v3, v3
	s_nop 0
	v_add_f32_e32 v3, 1.0, v3
	v_rcp_f32_e32 v3, v3
	s_nop 0
	v_mul_f32_e32 v5, v2, v3
	v_mul_f32_e32 v2, v8, v0
	v_fma_f32 v2, v16, v2, v22
	v_mul_f32_e32 v3, 0xbfb8aa3b, v2
	v_exp_f32_e32 v3, v3
	v_cvt_pk_bf16_f32 v4, v4, v5
	s_nop 0
	v_add_f32_e32 v3, 1.0, v3
	v_rcp_f32_e32 v3, v3
	s_nop 0
	v_mul_f32_e32 v6, v2, v3
	v_mul_f32_e32 v2, v9, v0
	v_fma_f32 v81, v17, v2, v23
	v_mul_f32_e32 v2, 0xbfb8aa3b, v81
	v_exp_f32_e32 v2, v2
	s_nop 0
	v_add_f32_e32 v2, 1.0, v2
	v_rcp_f32_e32 v2, v2
	s_nop 0
	v_mul_f32_e32 v7, v81, v2
	v_mul_f32_e32 v2, v82, v0
	v_mul_f32_e32 v0, v83, v0
	v_fma_f32 v2, v18, v2, v10
	v_fma_f32 v87, v19, v0, v11
	v_mul_f32_e32 v3, 0xbfb8aa3b, v2
	v_mul_f32_e32 v0, 0xbfb8aa3b, v87
	v_exp_f32_e32 v3, v3
	v_exp_f32_e32 v0, v0
	v_add_f32_e32 v3, 1.0, v3
	v_add_f32_e32 v0, 1.0, v0
	v_rcp_f32_e32 v3, v3
	v_rcp_f32_e32 v0, v0
	v_mul_f32_e32 v8, v2, v3
	v_mul_f32_e32 v0, v87, v0
	v_lshl_add_u64 v[2:3], v[76:77], 0, s[0:1]
	global_store_dword v[2:3], v4, off offset:1280
	v_cvt_pk_bf16_f32 v4, v6, v7
	global_store_dword v[2:3], v4, off offset:1284
	v_cvt_pk_bf16_f32 v0, v8, v0
	s_mul_i32 s0, s91, 0x600
	global_store_dword v[2:3], v0, off offset:1288
	v_add_u32_e32 v0, s0, v12
	ds_read2_b64 v[2:5], v0 offset1:1
	s_add_i32 s0, s13, s91
	s_ashr_i32 s1, s0, 31
	s_lshl_b64 s[0:1], s[0:1], 11
	s_waitcnt lgkmcnt(0)
	v_add_f32_e32 v6, 0, v2
	v_add_f32_e32 v8, v6, v3
	ds_read_b64 v[6:7], v0 offset:16
	v_add_f32_e32 v8, v8, v4
	v_add_f32_e32 v8, v8, v5
	s_waitcnt lgkmcnt(0)
	v_add_f32_e32 v8, v8, v6
	v_add_f32_e32 v8, v8, v7
	s_nop 0
	s_waitcnt lgkmcnt(0)
	s_nop 1
	v_add_f32_dpp v8, v8, v8 quad_perm:[1,0,3,2] row_mask:0xf bank_mask:0xf
	s_nop 0
	s_waitcnt lgkmcnt(0)
	s_nop 1
	v_add_f32_dpp v8, v8, v8 quad_perm:[2,3,0,1] row_mask:0xf bank_mask:0xf
	s_nop 0
	s_waitcnt lgkmcnt(0)
	s_nop 1
	v_add_f32_dpp v8, v8, v8 row_half_mirror row_mask:0xf bank_mask:0xf
	s_nop 0
	s_waitcnt lgkmcnt(0)
	s_nop 1
	v_add_f32_dpp v8, v8, v8 row_mirror row_mask:0xf bank_mask:0xf
	v_mov_b32_e32 v9, v8
	s_nop 1
	v_permlane16_swap_b32_e32 v8, v9
	s_waitcnt lgkmcnt(0)
	v_add_f32_e32 v8, v8, v9
	v_mov_b32_e32 v9, v8
	s_nop 1
	v_permlane32_swap_b32_e32 v8, v9
	s_waitcnt lgkmcnt(0)
	v_add_f32_e32 v9, v8, v9
	v_fmac_f32_e32 v3, 0xbb2aaaab, v9
	v_mul_f32_e32 v8, 0x3b2aaaab, v9
	v_fmamk_f32 v2, v9, 0xbb2aaaab, v2
	v_mul_f32_e32 v9, v3, v3
	v_fmac_f32_e32 v9, v2, v2
	v_pk_add_f32 v[82:83], v[4:5], v[8:9] op_sel_hi:[1,0] neg_lo:[0,1] neg_hi:[0,1]
	s_nop 0
	v_pk_mul_f32 v[4:5], v[82:83], v[82:83]
	s_nop 0
	v_add_f32_e32 v4, v4, v9
	v_pk_add_f32 v[8:9], v[6:7], v[8:9] op_sel_hi:[1,0] neg_lo:[0,1] neg_hi:[0,1]
	v_add_f32_e32 v78, v5, v4
	v_pk_mul_f32 v[4:5], v[8:9], v[8:9]
	s_nop 0
	v_add_f32_e32 v4, v4, v78
	v_add_f32_e32 v4, v5, v4
	s_nop 0
	s_waitcnt lgkmcnt(0)
	s_nop 1
	v_add_f32_dpp v4, v4, v4 quad_perm:[1,0,3,2] row_mask:0xf bank_mask:0xf
	s_nop 0
	s_waitcnt lgkmcnt(0)
	s_nop 1
	v_add_f32_dpp v4, v4, v4 quad_perm:[2,3,0,1] row_mask:0xf bank_mask:0xf
	s_nop 0
	s_waitcnt lgkmcnt(0)
	s_nop 1
	v_add_f32_dpp v4, v4, v4 row_half_mirror row_mask:0xf bank_mask:0xf
	s_nop 0
	s_waitcnt lgkmcnt(0)
	s_nop 1
	v_add_f32_dpp v4, v4, v4 row_mirror row_mask:0xf bank_mask:0xf
	v_mov_b32_e32 v5, v4
	s_nop 1
	v_permlane16_swap_b32_e32 v4, v5
	s_waitcnt lgkmcnt(0)
	v_add_f32_e32 v4, v4, v5
	v_mov_b32_e32 v5, v4
	s_nop 1
	v_permlane32_swap_b32_e32 v4, v5
	s_waitcnt lgkmcnt(0)
	v_add_f32_e32 v4, v4, v5
	v_fmamk_f32 v4, v4, 0x3b2aaaab, v162
	v_cmp_gt_f32_e64 s[42:43], s11, v4
	v_mul_f32_e32 v5, 0x4b800000, v4
	s_nop 0
	v_cndmask_b32_e64 v4, v4, v5, s[42:43]
	v_rsq_f32_e32 v4, v4
	s_nop 0
	v_mul_f32_e32 v5, 0x45800000, v4
	v_cndmask_b32_e64 v88, v4, v5, s[42:43]
	v_mul_f32_e32 v2, v2, v88
	v_mul_f32_e32 v3, v3, v88
	v_fma_f32 v2, v14, v2, v20
	v_mul_f32_e32 v4, 0xbfb8aa3b, v2
	v_exp_f32_e32 v4, v4
	v_fma_f32 v3, v15, v3, v21
	v_add_f32_e32 v4, 1.0, v4
	v_rcp_f32_e32 v4, v4
	s_nop 0
	v_mul_f32_e32 v2, v2, v4
	v_mul_f32_e32 v4, 0xbfb8aa3b, v3
	v_exp_f32_e32 v4, v4
	s_nop 0
	v_add_f32_e32 v4, 1.0, v4
	v_rcp_f32_e32 v4, v4
	s_nop 0
	v_mul_f32_e32 v3, v3, v4
	v_mul_f32_e32 v4, v82, v88
	v_fma_f32 v4, v16, v4, v22
	v_mul_f32_e32 v5, 0xbfb8aa3b, v4
	v_exp_f32_e32 v5, v5
	v_mul_f32_e32 v6, v8, v88
	v_fma_f32 v6, v18, v6, v10
	v_cvt_pk_bf16_f32 v2, v2, v3
	v_add_f32_e32 v5, 1.0, v5
	v_rcp_f32_e32 v5, v5
	s_nop 0
	v_mul_f32_e32 v4, v4, v5
	v_mul_f32_e32 v5, v83, v88
	v_fma_f32 v81, v17, v5, v23
	v_mul_f32_e32 v7, 0xbfb8aa3b, v6
	v_exp_f32_e32 v7, v7
	v_mul_f32_e32 v5, 0xbfb8aa3b, v81
	v_exp_f32_e32 v5, v5
	v_add_f32_e32 v7, 1.0, v7
	v_rcp_f32_e32 v7, v7
	v_add_f32_e32 v5, 1.0, v5
	v_rcp_f32_e32 v5, v5
	v_mul_f32_e32 v6, v6, v7
	v_mul_f32_e32 v7, v9, v88
	v_fma_f32 v87, v19, v7, v11
	v_mul_f32_e32 v7, 0xbfb8aa3b, v87
	v_exp_f32_e32 v7, v7
	v_lshl_add_u64 v[8:9], v[76:77], 0, s[0:1]
	v_mul_f32_e32 v5, v81, v5
	global_store_dword v[8:9], v2, off offset:1280
	v_add_f32_e32 v7, 1.0, v7
	v_rcp_f32_e32 v7, v7
	v_cvt_pk_bf16_f32 v2, v4, v5
	global_store_dword v[8:9], v2, off offset:1284
	s_add_i32 s0, s13, s93
	v_mul_f32_e32 v7, v87, v7
	v_cvt_pk_bf16_f32 v2, v6, v7
	global_store_dword v[8:9], v2, off offset:1288
	ds_read2_b64 v[2:5], v0 offset0:192 offset1:193
	s_ashr_i32 s1, s0, 31
	s_lshl_b64 s[0:1], s[0:1], 11
	s_waitcnt lgkmcnt(0)
	v_add_f32_e32 v6, 0, v2
	v_add_f32_e32 v8, v6, v3
	ds_read_b64 v[6:7], v0 offset:1552
	v_add_f32_e32 v8, v8, v4
	v_add_f32_e32 v8, v8, v5
	s_waitcnt lgkmcnt(0)
	v_add_f32_e32 v8, v8, v6
	v_add_f32_e32 v8, v8, v7
	s_nop 0
	s_waitcnt lgkmcnt(0)
	s_nop 1
	v_add_f32_dpp v8, v8, v8 quad_perm:[1,0,3,2] row_mask:0xf bank_mask:0xf
	s_nop 0
	s_waitcnt lgkmcnt(0)
	s_nop 1
	v_add_f32_dpp v8, v8, v8 quad_perm:[2,3,0,1] row_mask:0xf bank_mask:0xf
	s_nop 0
	s_waitcnt lgkmcnt(0)
	s_nop 1
	v_add_f32_dpp v8, v8, v8 row_half_mirror row_mask:0xf bank_mask:0xf
	s_nop 0
	s_waitcnt lgkmcnt(0)
	s_nop 1
	v_add_f32_dpp v8, v8, v8 row_mirror row_mask:0xf bank_mask:0xf
	v_mov_b32_e32 v9, v8
	s_nop 1
	v_permlane16_swap_b32_e32 v8, v9
	s_waitcnt lgkmcnt(0)
	v_add_f32_e32 v8, v8, v9
	v_mov_b32_e32 v9, v8
	s_nop 1
	v_permlane32_swap_b32_e32 v8, v9
	s_waitcnt lgkmcnt(0)
	v_add_f32_e32 v9, v8, v9
	v_fmac_f32_e32 v3, 0xbb2aaaab, v9
	v_mul_f32_e32 v8, 0x3b2aaaab, v9
	v_fmamk_f32 v2, v9, 0xbb2aaaab, v2
	v_mul_f32_e32 v9, v3, v3
	v_fmac_f32_e32 v9, v2, v2
	v_pk_add_f32 v[82:83], v[4:5], v[8:9] op_sel_hi:[1,0] neg_lo:[0,1] neg_hi:[0,1]
	s_nop 0
	v_pk_mul_f32 v[4:5], v[82:83], v[82:83]
	s_nop 0
	v_add_f32_e32 v4, v4, v9
	v_pk_add_f32 v[8:9], v[6:7], v[8:9] op_sel_hi:[1,0] neg_lo:[0,1] neg_hi:[0,1]
	v_add_f32_e32 v78, v5, v4
	v_pk_mul_f32 v[4:5], v[8:9], v[8:9]
	s_nop 0
	v_add_f32_e32 v4, v4, v78
	v_add_f32_e32 v4, v5, v4
	s_nop 0
	s_waitcnt lgkmcnt(0)
	s_nop 1
	v_add_f32_dpp v4, v4, v4 quad_perm:[1,0,3,2] row_mask:0xf bank_mask:0xf
	s_nop 0
	s_waitcnt lgkmcnt(0)
	s_nop 1
	v_add_f32_dpp v4, v4, v4 quad_perm:[2,3,0,1] row_mask:0xf bank_mask:0xf
	s_nop 0
	s_waitcnt lgkmcnt(0)
	s_nop 1
	v_add_f32_dpp v4, v4, v4 row_half_mirror row_mask:0xf bank_mask:0xf
	s_nop 0
	s_waitcnt lgkmcnt(0)
	s_nop 1
	v_add_f32_dpp v4, v4, v4 row_mirror row_mask:0xf bank_mask:0xf
	v_mov_b32_e32 v5, v4
	s_nop 1
	v_permlane16_swap_b32_e32 v4, v5
	s_waitcnt lgkmcnt(0)
	v_add_f32_e32 v4, v4, v5
	v_mov_b32_e32 v5, v4
	s_nop 1
	v_permlane32_swap_b32_e32 v4, v5
	s_waitcnt lgkmcnt(0)
	v_add_f32_e32 v4, v4, v5
	v_fmamk_f32 v4, v4, 0x3b2aaaab, v162
	v_cmp_gt_f32_e64 s[42:43], s11, v4
	v_mul_f32_e32 v5, 0x4b800000, v4
	s_nop 0
	v_cndmask_b32_e64 v4, v4, v5, s[42:43]
	v_rsq_f32_e32 v4, v4
	s_nop 0
	v_mul_f32_e32 v5, 0x45800000, v4
	v_cndmask_b32_e64 v88, v4, v5, s[42:43]
	v_mul_f32_e32 v2, v2, v88
	v_fma_f32 v2, v14, v2, v20
	v_mul_f32_e32 v4, 0xbfb8aa3b, v2
	v_exp_f32_e32 v4, v4
	s_nop 0
	v_add_f32_e32 v4, 1.0, v4
	v_rcp_f32_e32 v4, v4
	s_nop 0
	v_mul_f32_e32 v4, v2, v4
	v_mul_f32_e32 v2, v3, v88
	v_fma_f32 v2, v15, v2, v21
	v_mul_f32_e32 v3, 0xbfb8aa3b, v2
	v_exp_f32_e32 v3, v3
	s_nop 0
	v_add_f32_e32 v3, 1.0, v3
	v_rcp_f32_e32 v3, v3
	s_nop 0
	v_mul_f32_e32 v5, v2, v3
	v_mul_f32_e32 v2, v82, v88
	v_fma_f32 v2, v16, v2, v22
	v_mul_f32_e32 v3, 0xbfb8aa3b, v2
	v_exp_f32_e32 v3, v3
	v_cvt_pk_bf16_f32 v4, v4, v5
	s_nop 0
	v_add_f32_e32 v3, 1.0, v3
	v_rcp_f32_e32 v3, v3
	s_nop 0
	v_mul_f32_e32 v6, v2, v3
	v_mul_f32_e32 v2, v83, v88
	v_fma_f32 v81, v17, v2, v23
	v_mul_f32_e32 v2, 0xbfb8aa3b, v81
	v_exp_f32_e32 v2, v2
	s_nop 0
	v_add_f32_e32 v2, 1.0, v2
	v_rcp_f32_e32 v2, v2
	s_nop 0
	v_mul_f32_e32 v7, v81, v2
	v_mul_f32_e32 v2, v8, v88
	v_fma_f32 v2, v18, v2, v10
	v_mul_f32_e32 v3, 0xbfb8aa3b, v2
	v_exp_f32_e32 v3, v3
	s_nop 0
	v_add_f32_e32 v3, 1.0, v3
	v_rcp_f32_e32 v3, v3
	s_nop 0
	v_mul_f32_e32 v8, v2, v3
	v_mul_f32_e32 v2, v9, v88
	v_fma_f32 v87, v19, v2, v11
	v_mul_f32_e32 v2, 0xbfb8aa3b, v87
	v_exp_f32_e32 v2, v2
	s_nop 0
	v_add_f32_e32 v2, 1.0, v2
	v_rcp_f32_e32 v2, v2
	s_nop 0
	v_mul_f32_e32 v9, v87, v2
	v_lshl_add_u64 v[2:3], v[76:77], 0, s[0:1]
	global_store_dword v[2:3], v4, off offset:1280
	v_cvt_pk_bf16_f32 v4, v6, v7
	global_store_dword v[2:3], v4, off offset:1284
	v_cvt_pk_bf16_f32 v4, v8, v9
	global_store_dword v[2:3], v4, off offset:1288
	v_add_u32_e32 v2, 0xc00, v0
	ds_read2_b64 v[2:5], v2 offset1:1
	s_add_i32 s0, s13, s28
	s_ashr_i32 s1, s0, 31
	s_lshl_b64 s[0:1], s[0:1], 11
	s_cmpk_lt_i32 s12, 0x400
	s_waitcnt lgkmcnt(0)
	v_add_f32_e32 v6, 0, v2
	v_add_f32_e32 v8, v6, v3
	ds_read_b64 v[6:7], v0 offset:3088
	v_add_f32_e32 v0, v8, v4
	v_add_f32_e32 v0, v0, v5
	s_waitcnt lgkmcnt(0)
	v_add_f32_e32 v0, v0, v6
	v_add_f32_e32 v0, v0, v7
	s_nop 0
	s_waitcnt lgkmcnt(0)
	s_nop 1
	v_add_f32_dpp v0, v0, v0 quad_perm:[1,0,3,2] row_mask:0xf bank_mask:0xf
	s_nop 0
	s_waitcnt lgkmcnt(0)
	s_nop 1
	v_add_f32_dpp v0, v0, v0 quad_perm:[2,3,0,1] row_mask:0xf bank_mask:0xf
	s_nop 0
	s_waitcnt lgkmcnt(0)
	s_nop 1
	v_add_f32_dpp v0, v0, v0 row_half_mirror row_mask:0xf bank_mask:0xf
	s_nop 0
	s_waitcnt lgkmcnt(0)
	s_nop 1
	v_add_f32_dpp v0, v0, v0 row_mirror row_mask:0xf bank_mask:0xf
	v_mov_b32_e32 v8, v0
	s_nop 1
	v_permlane16_swap_b32_e32 v0, v8
	s_waitcnt lgkmcnt(0)
	v_add_f32_e32 v0, v0, v8
	v_mov_b32_e32 v8, v0
	s_nop 1
	v_permlane32_swap_b32_e32 v0, v8
	s_waitcnt lgkmcnt(0)
	v_add_f32_e32 v8, v0, v8
	v_mul_f32_e32 v0, 0x3b2aaaab, v8
	v_fmac_f32_e32 v3, 0xbb2aaaab, v8
	v_fmamk_f32 v2, v8, 0xbb2aaaab, v2
	v_mul_f32_e32 v78, v3, v3
	v_pk_add_f32 v[8:9], v[4:5], v[0:1] op_sel_hi:[1,0] neg_lo:[0,1] neg_hi:[0,1]
	v_fmac_f32_e32 v78, v2, v2
	v_pk_mul_f32 v[4:5], v[8:9], v[8:9]
	v_pk_add_f32 v[82:83], v[6:7], v[0:1] op_sel_hi:[1,0] neg_lo:[0,1] neg_hi:[0,1]
	v_add_f32_e32 v4, v4, v78
	v_add_f32_e32 v78, v5, v4
	v_pk_mul_f32 v[4:5], v[82:83], v[82:83]
	s_nop 0
	v_add_f32_e32 v0, v4, v78
	v_add_f32_e32 v0, v5, v0
	s_nop 0
	s_waitcnt lgkmcnt(0)
	s_nop 1
	v_add_f32_dpp v0, v0, v0 quad_perm:[1,0,3,2] row_mask:0xf bank_mask:0xf
	s_nop 0
	s_waitcnt lgkmcnt(0)
	s_nop 1
	v_add_f32_dpp v0, v0, v0 quad_perm:[2,3,0,1] row_mask:0xf bank_mask:0xf
	s_nop 0
	s_waitcnt lgkmcnt(0)
	s_nop 1
	v_add_f32_dpp v0, v0, v0 row_half_mirror row_mask:0xf bank_mask:0xf
	s_nop 0
	s_waitcnt lgkmcnt(0)
	s_nop 1
	v_add_f32_dpp v0, v0, v0 row_mirror row_mask:0xf bank_mask:0xf
	v_mov_b32_e32 v4, v0
	s_nop 1
	v_permlane16_swap_b32_e32 v0, v4
	s_waitcnt lgkmcnt(0)
	v_add_f32_e32 v0, v0, v4
	v_mov_b32_e32 v4, v0
	s_nop 1
	v_permlane32_swap_b32_e32 v0, v4
	s_waitcnt lgkmcnt(0)
	v_add_f32_e32 v0, v0, v4
	v_fmamk_f32 v0, v0, 0x3b2aaaab, v162
	v_cmp_gt_f32_e64 s[42:43], s11, v0
	v_mul_f32_e32 v4, 0x4b800000, v0
	s_nop 0
	v_cndmask_b32_e64 v0, v0, v4, s[42:43]
	v_rsq_f32_e32 v0, v0
	s_nop 0
	v_mul_f32_e32 v4, 0x45800000, v0
	v_cndmask_b32_e64 v0, v0, v4, s[42:43]
	v_mul_f32_e32 v2, v2, v0
	v_fma_f32 v2, v14, v2, v20
	v_mul_f32_e32 v4, 0xbfb8aa3b, v2
	v_exp_f32_e32 v4, v4
	s_nop 0
	v_add_f32_e32 v4, 1.0, v4
	v_rcp_f32_e32 v4, v4
	s_nop 0
	v_mul_f32_e32 v4, v2, v4
	v_mul_f32_e32 v2, v3, v0
	v_fma_f32 v2, v15, v2, v21
	v_mul_f32_e32 v3, 0xbfb8aa3b, v2
	v_exp_f32_e32 v3, v3
	s_nop 0
	v_add_f32_e32 v3, 1.0, v3
	v_rcp_f32_e32 v3, v3
	s_nop 0
	v_mul_f32_e32 v5, v2, v3
	v_mul_f32_e32 v2, v8, v0
	v_fma_f32 v2, v16, v2, v22
	v_mul_f32_e32 v3, 0xbfb8aa3b, v2
	v_exp_f32_e32 v3, v3
	v_cvt_pk_bf16_f32 v4, v4, v5
	s_nop 0
	v_add_f32_e32 v3, 1.0, v3
	v_rcp_f32_e32 v3, v3
	s_nop 0
	v_mul_f32_e32 v6, v2, v3
	v_mul_f32_e32 v2, v9, v0
	v_fma_f32 v81, v17, v2, v23
	v_mul_f32_e32 v2, 0xbfb8aa3b, v81
	v_exp_f32_e32 v2, v2
	s_nop 0
	v_add_f32_e32 v2, 1.0, v2
	v_rcp_f32_e32 v2, v2
	s_nop 0
	v_mul_f32_e32 v7, v81, v2
	v_mul_f32_e32 v2, v82, v0
	v_mul_f32_e32 v0, v83, v0
	v_fma_f32 v2, v18, v2, v10
	v_fma_f32 v87, v19, v0, v11
	v_mul_f32_e32 v3, 0xbfb8aa3b, v2
	v_mul_f32_e32 v0, 0xbfb8aa3b, v87
	v_exp_f32_e32 v3, v3
	v_exp_f32_e32 v0, v0
	v_add_f32_e32 v3, 1.0, v3
	v_add_f32_e32 v0, 1.0, v0
	v_rcp_f32_e32 v3, v3
	v_rcp_f32_e32 v0, v0
	v_mul_f32_e32 v8, v2, v3
	v_mul_f32_e32 v0, v87, v0
	v_lshl_add_u64 v[2:3], v[76:77], 0, s[0:1]
	global_store_dword v[2:3], v4, off offset:1280
	v_cvt_pk_bf16_f32 v4, v6, v7
	global_store_dword v[2:3], v4, off offset:1284
	v_cvt_pk_bf16_f32 v0, v8, v0
	global_store_dword v[2:3], v0, off offset:1288
	s_cbranch_scc0 .LBB7_813

.LBB7_811:
	s_or_b64 exec, exec, s[0:1]
	s_waitcnt lgkmcnt(0)
	s_barrier
	s_add_i32 s15, s12, s60
	s_cmp_lt_i32 s15, s100
	s_cselect_b32 s15, s15, s101
	s_cmpk_lt_i32 s15, 0x400
	s_cbranch_scc0 .Lcpf_skip
	s_movk_i32 s14, 0x1a0
	v_cmp_gt_i32_e64 s[6:7], s14, v150
	s_lshl_b32 s15, s15, 5
	s_and_b32 s3, s15, 0x7e0
	s_sub_i32 s3, 29, s3
	s_sub_i32 s4, s15, 30
	s_mov_b32 s5, 0x2aaaaaab
	s_movk_i32 s14, 0xfe80
	v_mov_b32_e32 v79, v150
	v_mul_hi_i32 v80, v79, s5
	v_lshrrev_b32_e32 v81, 31, v80
	v_ashrrev_i32_e32 v80, 3, v80
	v_add_u32_e32 v80, v80, v81
	v_cmp_lt_i32_e64 s[42:43], s3, v80
	s_nop 1
	s_and_saveexec_b64 s[8:9], s[42:43]
	v_add_u32_e32 v82, s4, v80
	v_ashrrev_i32_e32 v83, 31, v82
	v_lshlrev_b64 v[82:83], 11, v[82:83]
	v_lshl_add_u64 v[82:83], s[44:45], 0, v[82:83]
	v_lshlrev_b32_e32 v84, 3, v79
	v_mad_i32_i24 v84, v80, s14, v84
	v_mov_b32_e32 v85, 0
	v_lshl_add_u64 v[82:83], v[84:85], 1, v[82:83]
	global_load_dwordx4 v[24:27], v[82:83], off offset:512
	global_load_dwordx4 v[28:31], v[82:83], off offset:1280
	s_or_b64 exec, exec, s[8:9]
	v_add_u32_e32 v79, 512, v150
	v_mul_hi_i32 v80, v79, s5
	v_lshrrev_b32_e32 v81, 31, v80
	v_ashrrev_i32_e32 v80, 3, v80
	v_add_u32_e32 v80, v80, v81
	v_cmp_lt_i32_e64 s[42:43], s3, v80
	s_nop 1
	s_and_saveexec_b64 s[8:9], s[42:43]
	v_add_u32_e32 v82, s4, v80
	v_ashrrev_i32_e32 v83, 31, v82
	v_lshlrev_b64 v[82:83], 11, v[82:83]
	v_lshl_add_u64 v[82:83], s[44:45], 0, v[82:83]
	v_lshlrev_b32_e32 v84, 3, v79
	v_mad_i32_i24 v84, v80, s14, v84
	v_mov_b32_e32 v85, 0
	v_lshl_add_u64 v[82:83], v[84:85], 1, v[82:83]
	global_load_dwordx4 v[32:35], v[82:83], off offset:512
	global_load_dwordx4 v[36:39], v[82:83], off offset:1280
	s_or_b64 exec, exec, s[8:9]
	v_add_u32_e32 v79, 1024, v150
	v_mul_hi_i32 v80, v79, s5
	v_lshrrev_b32_e32 v81, 31, v80
	v_ashrrev_i32_e32 v80, 3, v80
	v_add_u32_e32 v80, v80, v81
	v_cmp_lt_i32_e64 s[42:43], s3, v80
	s_nop 1
	s_and_saveexec_b64 s[8:9], s[42:43]
	v_add_u32_e32 v82, s4, v80
	v_ashrrev_i32_e32 v83, 31, v82
	v_lshlrev_b64 v[82:83], 11, v[82:83]
	v_lshl_add_u64 v[82:83], s[44:45], 0, v[82:83]
	v_lshlrev_b32_e32 v84, 3, v79
	v_mad_i32_i24 v84, v80, s14, v84
	v_mov_b32_e32 v85, 0
	v_lshl_add_u64 v[82:83], v[84:85], 1, v[82:83]
	global_load_dwordx4 v[40:43], v[82:83], off offset:512
	global_load_dwordx4 v[44:47], v[82:83], off offset:1280
	s_or_b64 exec, exec, s[8:9]
	v_add_u32_e32 v79, 1536, v150
	v_mul_hi_i32 v80, v79, s5
	v_lshrrev_b32_e32 v81, 31, v80
	v_ashrrev_i32_e32 v80, 3, v80
	v_add_u32_e32 v80, v80, v81
	v_cmp_lt_i32_e64 s[42:43], s3, v80
	s_nop 1
	s_and_saveexec_b64 s[8:9], s[42:43]
	v_add_u32_e32 v82, s4, v80
	v_ashrrev_i32_e32 v83, 31, v82
	v_lshlrev_b64 v[82:83], 11, v[82:83]
	v_lshl_add_u64 v[82:83], s[44:45], 0, v[82:83]
	v_lshlrev_b32_e32 v84, 3, v79
	v_mad_i32_i24 v84, v80, s14, v84
	v_mov_b32_e32 v85, 0
	v_lshl_add_u64 v[82:83], v[84:85], 1, v[82:83]
	global_load_dwordx4 v[48:51], v[82:83], off offset:512
	global_load_dwordx4 v[52:55], v[82:83], off offset:1280
	s_or_b64 exec, exec, s[8:9]
	v_add_u32_e32 v79, 2048, v150
	v_mul_hi_i32 v80, v79, s5
	v_lshrrev_b32_e32 v81, 31, v80
	v_ashrrev_i32_e32 v80, 3, v80
	v_add_u32_e32 v80, v80, v81
	v_cmp_lt_i32_e64 s[42:43], s3, v80
	s_nop 1
	s_and_saveexec_b64 s[8:9], s[42:43]
	v_add_u32_e32 v82, s4, v80
	v_ashrrev_i32_e32 v83, 31, v82
	v_lshlrev_b64 v[82:83], 11, v[82:83]
	v_lshl_add_u64 v[82:83], s[44:45], 0, v[82:83]
	v_lshlrev_b32_e32 v84, 3, v79
	v_mad_i32_i24 v84, v80, s14, v84
	v_mov_b32_e32 v85, 0
	v_lshl_add_u64 v[82:83], v[84:85], 1, v[82:83]
	global_load_dwordx4 v[56:59], v[82:83], off offset:512
	global_load_dwordx4 v[60:63], v[82:83], off offset:1280
	s_or_b64 exec, exec, s[8:9]
	v_add_u32_e32 v79, 2560, v150
	v_mul_hi_i32 v80, v79, s5
	v_lshrrev_b32_e32 v81, 31, v80
	v_ashrrev_i32_e32 v80, 3, v80
	v_add_u32_e32 v80, v80, v81
	v_cmp_lt_i32_e64 s[42:43], s3, v80
	s_nop 1
	s_and_b64 s[42:43], s[42:43], s[6:7]
	s_and_saveexec_b64 s[8:9], s[42:43]
	v_add_u32_e32 v82, s4, v80
	v_ashrrev_i32_e32 v83, 31, v82
	v_lshlrev_b64 v[82:83], 11, v[82:83]
	v_lshl_add_u64 v[82:83], s[44:45], 0, v[82:83]
	v_lshlrev_b32_e32 v84, 3, v79
	v_mad_i32_i24 v84, v80, s14, v84
	v_mov_b32_e32 v85, 0
	v_lshl_add_u64 v[82:83], v[84:85], 1, v[82:83]
	global_load_dwordx4 v[64:67], v[82:83], off offset:512
	global_load_dwordx4 v[68:71], v[82:83], off offset:1280
	s_or_b64 exec, exec, s[8:9]

	.amdhsa_kernel _ZN2mk6mk_fwdENS_4ArgsE
		.amdhsa_group_segment_fixed_size 0
		.amdhsa_private_segment_fixed_size 0
		.amdhsa_kernarg_size 560
		.amdhsa_user_sgpr_count 2
		.amdhsa_user_sgpr_dispatch_ptr 0
		.amdhsa_user_sgpr_queue_ptr 0
		.amdhsa_user_sgpr_kernarg_segment_ptr 1
		.amdhsa_user_sgpr_dispatch_id 0
		.amdhsa_user_sgpr_kernarg_preload_length 0
		.amdhsa_user_sgpr_kernarg_preload_offset 0
		.amdhsa_user_sgpr_private_segment_size 0
		.amdhsa_uses_dynamic_stack 0
		.amdhsa_enable_private_segment 0
		.amdhsa_system_sgpr_workgroup_id_x 1
		.amdhsa_system_sgpr_workgroup_id_y 0
		.amdhsa_system_sgpr_workgroup_id_z 0
		.amdhsa_system_sgpr_workgroup_info 0
		.amdhsa_system_vgpr_workitem_id 2
		.amdhsa_next_free_vgpr 255
		.amdhsa_next_free_sgpr 102
		.amdhsa_accum_offset 256
		.amdhsa_reserve_vcc 1
		.amdhsa_float_round_mode_32 0
		.amdhsa_float_round_mode_16_64 0
		.amdhsa_float_denorm_mode_32 3
		.amdhsa_float_denorm_mode_16_64 3
		.amdhsa_dx10_clamp 1
		.amdhsa_ieee_mode 1
		.amdhsa_fp16_overflow 0
		.amdhsa_tg_split 0
		.amdhsa_exception_fp_ieee_invalid_op 0
		.amdhsa_exception_fp_denorm_src 0
		.amdhsa_exception_fp_ieee_div_zero 0
		.amdhsa_exception_fp_ieee_overflow 0
		.amdhsa_exception_fp_ieee_underflow 0
		.amdhsa_exception_fp_ieee_inexact 0
		.amdhsa_exception_int_div_zero 0
	.end_amdhsa_kernel

amdhsa.kernels:
  - .agpr_count:     0
    .args:
      - .address_space:  global
        .offset:         0
        .size:           8
        .value_kind:     global_buffer
      - .address_space:  global
        .offset:         8
        .size:           8
        .value_kind:     global_buffer
      - .address_space:  global
        .offset:         16
        .size:           8
        .value_kind:     global_buffer
      - .offset:         24
        .size:           4
        .value_kind:     by_value
    .group_segment_fixed_size: 0
    .kernarg_segment_align: 8
    .kernarg_segment_size: 28
    .language:       OpenCL C
    .language_version:
      - 2
      - 0
    .max_flat_workgroup_size: 256
    .name:           _ZN2nv9rmsnorm_kEPKfS1_Pfi
    .private_segment_fixed_size: 0
    .sgpr_count:     14
    .sgpr_spill_count: 0
    .symbol:         _ZN2nv9rmsnorm_kEPKfS1_Pfi.kd
    .uniform_work_group_size: 1
    .uses_dynamic_stack: false
    .vgpr_count:     43
    .vgpr_spill_count: 0
    .wavefront_size: 64
  - .agpr_count:     0
    .args:
      - .address_space:  global
        .offset:         0
        .size:           8
        .value_kind:     global_buffer
      - .address_space:  global
        .offset:         8
        .size:           8
        .value_kind:     global_buffer
      - .offset:         16
        .size:           8
        .value_kind:     by_value
      - .offset:         24
        .size:           4
        .value_kind:     hidden_block_count_x
      - .offset:         28
        .size:           4
        .value_kind:     hidden_block_count_y
      - .offset:         32
        .size:           4
        .value_kind:     hidden_block_count_z
      - .offset:         36
        .size:           2
        .value_kind:     hidden_group_size_x
      - .offset:         38
        .size:           2
        .value_kind:     hidden_group_size_y
      - .offset:         40
        .size:           2
        .value_kind:     hidden_group_size_z
      - .offset:         42
        .size:           2
        .value_kind:     hidden_remainder_x
      - .offset:         44
        .size:           2
        .value_kind:     hidden_remainder_y
      - .offset:         46
        .size:           2
        .value_kind:     hidden_remainder_z
      - .offset:         64
        .size:           8
        .value_kind:     hidden_global_offset_x
      - .offset:         72
        .size:           8
        .value_kind:     hidden_global_offset_y
      - .offset:         80
        .size:           8
        .value_kind:     hidden_global_offset_z
      - .offset:         88
        .size:           2
        .value_kind:     hidden_grid_dims
    .group_segment_fixed_size: 0
    .kernarg_segment_align: 8
    .kernarg_segment_size: 280
    .language:       OpenCL C
    .language_version:
      - 2
      - 0
    .max_flat_workgroup_size: 1024
    .name:           _ZN2nv6copy_kEPK15HIP_vector_typeIfLj4EEPS1_m
    .private_segment_fixed_size: 0
    .sgpr_count:     18
    .sgpr_spill_count: 0
    .symbol:         _ZN2nv6copy_kEPK15HIP_vector_typeIfLj4EEPS1_m.kd
    .uniform_work_group_size: 1
    .uses_dynamic_stack: false
    .vgpr_count:     10
    .vgpr_spill_count: 0
    .wavefront_size: 64
  - .agpr_count:     0
    .args:
      - .address_space:  global
        .offset:         0
        .size:           8
        .value_kind:     global_buffer
      - .address_space:  global
        .offset:         8
        .size:           8
        .value_kind:     global_buffer
      - .address_space:  global
        .offset:         16
        .size:           8
        .value_kind:     global_buffer
      - .address_space:  global
        .offset:         24
        .size:           8
        .value_kind:     global_buffer
      - .address_space:  global
        .offset:         32
        .size:           8
        .value_kind:     global_buffer
      - .address_space:  global
        .offset:         40
        .size:           8
        .value_kind:     global_buffer
      - .address_space:  global
        .offset:         48
        .size:           8
        .value_kind:     global_buffer
      - .address_space:  global
        .offset:         56
        .size:           8
        .value_kind:     global_buffer
      - .address_space:  global
        .offset:         64
        .size:           8
        .value_kind:     global_buffer
      - .address_space:  global
        .offset:         72
        .size:           8
        .value_kind:     global_buffer
    .group_segment_fixed_size: 0
    .kernarg_segment_align: 8
    .kernarg_segment_size: 80
    .language:       OpenCL C
    .language_version:
      - 2
      - 0
    .max_flat_workgroup_size: 64
    .name:           _ZN2nv4s5_kEPKfS1_S1_S1_S1_S1_S1_S1_S1_Pf
    .private_segment_fixed_size: 0
    .sgpr_count:     60
    .sgpr_spill_count: 0
    .symbol:         _ZN2nv4s5_kEPKfS1_S1_S1_S1_S1_S1_S1_S1_Pf.kd
    .uniform_work_group_size: 1
    .uses_dynamic_stack: false
    .vgpr_count:     130
    .vgpr_spill_count: 0
    .wavefront_size: 64
  - .agpr_count:     0
    .args:
      - .address_space:  global
        .offset:         0
        .size:           8
        .value_kind:     global_buffer
      - .address_space:  global
        .offset:         8
        .size:           8
        .value_kind:     global_buffer
      - .offset:         16
        .size:           4
        .value_kind:     hidden_block_count_x
      - .offset:         20
        .size:           4
        .value_kind:     hidden_block_count_y
      - .offset:         24
        .size:           4
        .value_kind:     hidden_block_count_z
      - .offset:         28
        .size:           2
        .value_kind:     hidden_group_size_x
      - .offset:         30
        .size:           2
        .value_kind:     hidden_group_size_y
      - .offset:         32
        .size:           2
        .value_kind:     hidden_group_size_z
      - .offset:         34
        .size:           2
        .value_kind:     hidden_remainder_x
      - .offset:         36
        .size:           2
        .value_kind:     hidden_remainder_y
      - .offset:         38
        .size:           2
        .value_kind:     hidden_remainder_z
      - .offset:         56
        .size:           8
        .value_kind:     hidden_global_offset_x
      - .offset:         64
        .size:           8
        .value_kind:     hidden_global_offset_y
      - .offset:         72
        .size:           8
        .value_kind:     hidden_global_offset_z
      - .offset:         80
        .size:           2
        .value_kind:     hidden_grid_dims
    .group_segment_fixed_size: 0
    .kernarg_segment_align: 8
    .kernarg_segment_size: 272
    .language:       OpenCL C
    .language_version:
      - 2
      - 0
    .max_flat_workgroup_size: 1024
    .name:           _ZN2nv6pool_kEPKfPf
    .private_segment_fixed_size: 0
    .sgpr_count:     14
    .sgpr_spill_count: 0
    .symbol:         _ZN2nv6pool_kEPKfPf.kd
    .uniform_work_group_size: 1
    .uses_dynamic_stack: false
    .vgpr_count:     12
    .vgpr_spill_count: 0
    .wavefront_size: 64
  - .agpr_count:     0
    .args:
      - .address_space:  global
        .offset:         0
        .size:           8
        .value_kind:     global_buffer
      - .address_space:  global
        .offset:         8
        .size:           8
        .value_kind:     global_buffer
      - .address_space:  global
        .offset:         16
        .size:           8
        .value_kind:     global_buffer
      - .address_space:  global
        .offset:         24
        .size:           8
        .value_kind:     global_buffer
      - .offset:         32
        .size:           4
        .value_kind:     hidden_block_count_x
      - .offset:         36
        .size:           4
        .value_kind:     hidden_block_count_y
      - .offset:         40
        .size:           4
        .value_kind:     hidden_block_count_z
      - .offset:         44
        .size:           2
        .value_kind:     hidden_group_size_x
      - .offset:         46
        .size:           2
        .value_kind:     hidden_group_size_y
      - .offset:         48
        .size:           2
        .value_kind:     hidden_group_size_z
      - .offset:         50
        .size:           2
        .value_kind:     hidden_remainder_x
      - .offset:         52
        .size:           2
        .value_kind:     hidden_remainder_y
      - .offset:         54
        .size:           2
        .value_kind:     hidden_remainder_z
      - .offset:         72
        .size:           8
        .value_kind:     hidden_global_offset_x
      - .offset:         80
        .size:           8
        .value_kind:     hidden_global_offset_y
      - .offset:         88
        .size:           8
        .value_kind:     hidden_global_offset_z
      - .offset:         96
        .size:           2
        .value_kind:     hidden_grid_dims
    .group_segment_fixed_size: 0
    .kernarg_segment_align: 8
    .kernarg_segment_size: 288
    .language:       OpenCL C
    .language_version:
      - 2
      - 0
    .max_flat_workgroup_size: 1024
    .name:           _ZN2nv6conv_kEPKfS1_S1_Pf
    .private_segment_fixed_size: 0
    .sgpr_count:     18
    .sgpr_spill_count: 0
    .symbol:         _ZN2nv6conv_kEPKfS1_S1_Pf.kd
    .uniform_work_group_size: 1
    .uses_dynamic_stack: false
    .vgpr_count:     15
    .vgpr_spill_count: 0
    .wavefront_size: 64
  - .agpr_count:     0
    .args:
      - .address_space:  global
        .offset:         0
        .size:           8
        .value_kind:     global_buffer
      - .address_space:  global
        .offset:         8
        .size:           8
        .value_kind:     global_buffer
      - .address_space:  global
        .offset:         16
        .size:           8
        .value_kind:     global_buffer
      - .address_space:  global
        .offset:         24
        .size:           8
        .value_kind:     global_buffer
    .group_segment_fixed_size: 0
    .kernarg_segment_align: 8
    .kernarg_segment_size: 32
    .language:       OpenCL C
    .language_version:
      - 2
      - 0
    .max_flat_workgroup_size: 256
    .name:           _ZN2nv8convln_kEPKfS1_S1_Pf
    .private_segment_fixed_size: 0
    .sgpr_count:     18
    .sgpr_spill_count: 0
    .symbol:         _ZN2nv8convln_kEPKfS1_S1_Pf.kd
    .uniform_work_group_size: 1
    .uses_dynamic_stack: false
    .vgpr_count:     24
    .vgpr_spill_count: 0
    .wavefront_size: 64
  - .agpr_count:     0
    .args:
      - .address_space:  global
        .offset:         0
        .size:           8
        .value_kind:     global_buffer
      - .offset:         8
        .size:           8
        .value_kind:     by_value
    .group_segment_fixed_size: 0
    .kernarg_segment_align: 8
    .kernarg_segment_size: 16
    .language:       OpenCL C
    .language_version:
      - 2
      - 0
    .max_flat_workgroup_size: 256
    .name:           _ZN2nv9softmax_kEPfm
    .private_segment_fixed_size: 0
    .sgpr_count:     14
    .sgpr_spill_count: 0
    .symbol:         _ZN2nv9softmax_kEPfm.kd
    .uniform_work_group_size: 1
    .uses_dynamic_stack: false
    .vgpr_count:     16
    .vgpr_spill_count: 0
    .wavefront_size: 64
  - .agpr_count:     0
    .args:
      - .offset:         0
        .size:           304
        .value_kind:     by_value
      - .offset:         304
        .size:           4
        .value_kind:     hidden_block_count_x
      - .offset:         308
        .size:           4
        .value_kind:     hidden_block_count_y
      - .offset:         312
        .size:           4
        .value_kind:     hidden_block_count_z
      - .offset:         316
        .size:           2
        .value_kind:     hidden_group_size_x
      - .offset:         318
        .size:           2
        .value_kind:     hidden_group_size_y
      - .offset:         320
        .size:           2
        .value_kind:     hidden_group_size_z
      - .offset:         322
        .size:           2
        .value_kind:     hidden_remainder_x
      - .offset:         324
        .size:           2
        .value_kind:     hidden_remainder_y
      - .offset:         326
        .size:           2
        .value_kind:     hidden_remainder_z
      - .offset:         344
        .size:           8
        .value_kind:     hidden_global_offset_x
      - .offset:         352
        .size:           8
        .value_kind:     hidden_global_offset_y
      - .offset:         360
        .size:           8
        .value_kind:     hidden_global_offset_z
      - .offset:         368
        .size:           2
        .value_kind:     hidden_grid_dims
      - .offset:         392
        .size:           8
        .value_kind:     hidden_multigrid_sync_arg
      - .offset:         424
        .size:           4
        .value_kind:     hidden_dynamic_lds_size
    .group_segment_fixed_size: 0
    .kernarg_segment_align: 8
    .kernarg_segment_size: 560
    .language:       OpenCL C
    .language_version:
      - 2
      - 0
    .max_flat_workgroup_size: 512
    .name:           _ZN2mk6mk_fwdENS_4ArgsE
    .private_segment_fixed_size: 0
    .sgpr_count:     108
    .sgpr_spill_count: 290
    .symbol:         _ZN2mk6mk_fwdENS_4ArgsE.kd
    .uniform_work_group_size: 1
    .uses_dynamic_stack: false
    .vgpr_count:     255
    .vgpr_spill_count: 0
    .wavefront_size: 64
  - .agpr_count:     0
    .args:
      - .offset:         0
        .size:           144
        .value_kind:     by_value
    .group_segment_fixed_size: 13056
    .kernarg_segment_align: 8
    .kernarg_segment_size: 144
    .language:       OpenCL C
    .language_version:
      - 2
      - 0
    .max_flat_workgroup_size: 256
    .name:           _ZN2nv5ngemmILi2ELi0EEEvNS_5NGemmE
    .private_segment_fixed_size: 0
    .sgpr_count:     37
    .sgpr_spill_count: 0
    .symbol:         _ZN2nv5ngemmILi2ELi0EEEvNS_5NGemmE.kd
    .uniform_work_group_size: 1
    .uses_dynamic_stack: false
    .vgpr_count:     78
    .vgpr_spill_count: 0
    .wavefront_size: 64
  - .agpr_count:     0
    .args:
      - .offset:         0
        .size:           144
        .value_kind:     by_value
    .group_segment_fixed_size: 8704
    .kernarg_segment_align: 8
    .kernarg_segment_size: 144
    .language:       OpenCL C
    .language_version:
      - 2
      - 0
    .max_flat_workgroup_size: 256
    .name:           _ZN2nv5ngemmILi1ELi0EEEvNS_5NGemmE
    .private_segment_fixed_size: 0
    .sgpr_count:     40
    .sgpr_spill_count: 0
    .symbol:         _ZN2nv5ngemmILi1ELi0EEEvNS_5NGemmE.kd
    .uniform_work_group_size: 1
    .uses_dynamic_stack: false
    .vgpr_count:     66
    .vgpr_spill_count: 0
    .wavefront_size: 64
  - .agpr_count:     0
    .args:
      - .offset:         0
        .size:           144
        .value_kind:     by_value
    .group_segment_fixed_size: 8704
    .kernarg_segment_align: 8
    .kernarg_segment_size: 144
    .language:       OpenCL C
    .language_version:
      - 2
      - 0
    .max_flat_workgroup_size: 256
    .name:           _ZN2nv5ngemmILi0ELi0EEEvNS_5NGemmE
    .private_segment_fixed_size: 0
    .sgpr_count:     38
    .sgpr_spill_count: 0
    .symbol:         _ZN2nv5ngemmILi0ELi0EEEvNS_5NGemmE.kd
    .uniform_work_group_size: 1
    .uses_dynamic_stack: false
    .vgpr_count:     66
    .vgpr_spill_count: 0
    .wavefront_size: 64
  - .agpr_count:     0
    .args:
      - .offset:         0
        .size:           144
        .value_kind:     by_value
    .group_segment_fixed_size: 8704
    .kernarg_segment_align: 8
    .kernarg_segment_size: 144
    .language:       OpenCL C
    .language_version:
      - 2
      - 0
    .max_flat_workgroup_size: 256
    .name:           _ZN2nv5ngemmILi3ELi0EEEvNS_5NGemmE
    .private_segment_fixed_size: 0
    .sgpr_count:     41
    .sgpr_spill_count: 0
    .symbol:         _ZN2nv5ngemmILi3ELi0EEEvNS_5NGemmE.kd
    .uniform_work_group_size: 1
    .uses_dynamic_stack: false
    .vgpr_count:     68
    .vgpr_spill_count: 0
    .wavefront_size: 64
  - .agpr_count:     0
    .args:
      - .offset:         0
        .size:           144
        .value_kind:     by_value
    .group_segment_fixed_size: 8704
    .kernarg_segment_align: 8
    .kernarg_segment_size: 144
    .language:       OpenCL C
    .language_version:
      - 2
      - 0
    .max_flat_workgroup_size: 256
    .name:           _ZN2nv5ngemmILi4ELi0EEEvNS_5NGemmE
    .private_segment_fixed_size: 0
    .sgpr_count:     38
    .sgpr_spill_count: 0
    .symbol:         _ZN2nv5ngemmILi4ELi0EEEvNS_5NGemmE.kd
    .uniform_work_group_size: 1
    .uses_dynamic_stack: false
    .vgpr_count:     66
    .vgpr_spill_count: 0
    .wavefront_size: 64
  - .agpr_count:     0
    .args:
      - .offset:         0
        .size:           144
        .value_kind:     by_value
    .group_segment_fixed_size: 8704
    .kernarg_segment_align: 8
    .kernarg_segment_size: 144
    .language:       OpenCL C
    .language_version:
      - 2
      - 0
    .max_flat_workgroup_size: 256
    .name:           _ZN2nv5ngemmILi5ELi1EEEvNS_5NGemmE
    .private_segment_fixed_size: 0
    .sgpr_count:     37
    .sgpr_spill_count: 0
    .symbol:         _ZN2nv5ngemmILi5ELi1EEEvNS_5NGemmE.kd
    .uniform_work_group_size: 1
    .uses_dynamic_stack: false
    .vgpr_count:     68
    .vgpr_spill_count: 0
    .wavefront_size: 64
